# ATTN ping-pong v1 + section 7.4 static s_setprio 1 for waves 4-7 during the tile loop
# speedup vs baseline: 1.0009x; 1.0009x over previous
.LBB0_946:
	s_setprio 0
	s_cmp_lt_u32 s93, 4
	s_cbranch_scc0 .Lpp_post
	s_barrier

.LBB0_952:
	s_lshl_b32 s6, s5, 8
	s_add_i32 s14, s6, s16
	s_add_u32 s12, s8, s14
	s_addc_u32 s13, s9, 0
	s_lshl_b64 s[6:7], s[12:13], 10
	v_lshl_add_u64 v[4:5], v[114:115], 0, s[6:7]
	s_mov_b32 s15, s11
	global_load_dwordx4 v[98:101], v[4:5], off offset:32
	global_load_dwordx4 v[102:105], v[4:5], off offset:64
	global_load_dwordx4 v[106:109], v[4:5], off offset:96
	v_lshl_add_u64 v[136:137], s[14:15], 3, v[120:121]
	global_load_dwordx4 v[110:113], v[4:5], off
	global_load_dwordx2 v[138:139], v[136:137], off
	s_waitcnt lgkmcnt(0)
	s_barrier
	s_mov_b32 m0, s21
	global_load_lds_dwordx4 v[116:117], off
	s_mov_b32 m0, s22
	global_load_lds_dwordx4 v[118:119], off
	v_mov_b32_e32 v16, v2
	s_mov_b32 m0, s23
	global_load_lds_dwordx4 v[122:123], off
	s_mov_b32 m0, s24
	global_load_lds_dwordx4 v[124:125], off
	s_waitcnt vmcnt(2)
	v_mov_b32_e32 v17, v2
	s_lshl_b32 s6, s5, 2
	s_lshl_b32 s30, s5, 10
	v_mov_b32_e32 v3, v2
	v_mov_b32_e32 v4, v2
	v_mov_b32_e32 v5, v2
	v_mov_b32_e32 v6, v2
	v_mov_b32_e32 v7, v2
	v_mov_b32_e32 v8, v2
	v_mov_b32_e32 v9, v2
	v_mov_b32_e32 v10, v2
	v_mov_b32_e32 v11, v2
	v_mov_b32_e32 v12, v2
	v_mov_b32_e32 v13, v2
	v_mov_b32_e32 v14, v2
	v_mov_b32_e32 v15, v2
	v_mov_b64_e32 v[48:49], v[16:17]
	v_mov_b64_e32 v[32:33], v[16:17]
	v_mov_b64_e32 v[64:65], v[16:17]
	s_mov_b32 s15, 2
	s_add_i32 s27, s6, 4
	s_lshr_b32 s28, s14, 6
	s_or_b32 s29, s6, 3
	v_add_u32_e32 v148, s30, v142
	s_addk_i32 s30, 0x400
	s_mov_b32 s31, 0
	s_movk_i32 s33, 0xaf
	v_mov_b64_e32 v[46:47], v[14:15]
	v_mov_b64_e32 v[44:45], v[12:13]
	v_mov_b64_e32 v[42:43], v[10:11]
	v_mov_b64_e32 v[40:41], v[8:9]
	v_mov_b64_e32 v[38:39], v[6:7]
	v_mov_b64_e32 v[36:37], v[4:5]
	v_mov_b64_e32 v[34:35], v[2:3]
	v_mov_b64_e32 v[30:31], v[14:15]
	v_mov_b64_e32 v[28:29], v[12:13]
	v_mov_b64_e32 v[26:27], v[10:11]
	v_mov_b64_e32 v[24:25], v[8:9]
	v_mov_b64_e32 v[22:23], v[6:7]
	v_mov_b64_e32 v[20:21], v[4:5]
	v_mov_b64_e32 v[18:19], v[2:3]
	v_mov_b64_e32 v[62:63], v[14:15]
	v_mov_b64_e32 v[60:61], v[12:13]
	v_mov_b64_e32 v[58:59], v[10:11]
	v_mov_b64_e32 v[56:57], v[8:9]
	v_mov_b64_e32 v[54:55], v[6:7]
	v_mov_b64_e32 v[52:53], v[4:5]
	v_mov_b64_e32 v[50:51], v[2:3]
	s_mov_b32 s34, 0
	s_cmp_lt_u32 s93, 4
	s_cbranch_scc1 .Lpp_pre
	s_setprio 1
	s_barrier
